# combo12 + small-tiles-first chosen by bit 3 of the workgroup id (within-XCD stagger) instead of bit 0
# baseline (speedup 1.0000x reference)
; #define LAS __attribute__((address_space(3)))
; template <int KS, class Epi>
; __device__ __forceinline__ void small_gemm(const bf16_t* __restrict__ A, int lda, int a_grp_step, const bf16_t* __restrict__ Bt, int N, const Epi& E, LAS unsigned char* lds) {
;     constexpr int K = KS * 128;
;     const int lane = threadIdx.x & 63, wid = threadIdx.x >> 6, fr = lane & 15, fq = lane >> 4, th = wid >> 2, kq = wid & 3;
;     LAS f32x4* red = (LAS f32x4*)lds;
;     const int ntile = 16 * (N >> 5);
;     for (int pair = blockIdx.x; pair * 2 < ntile; pair += gridDim.x) {
;         const int tile = pair * 2 + th, tr = tile & 15, tc = tile >> 4, row0 = MP + tr * 32, col0 = tc * 32;
;         const bf16_t* ap = A + (size_t)(row0 + fr) * lda + (col0 >> 8) * a_grp_step + kq * (KS * 32) + 8 * fq;
;         const bf16_t* bp = Bt + (size_t)(col0 + fr) * K + kq * (KS * 32) + 8 * fq;
; __global__ void __launch_bounds__(512, 2) mega(Params p) {
;     ...
;     if (PH_ON(5)) { pg8::StaticOrder S; const bool sfirst = (blockIdx.x & 1) != 0;
;         if (sfirst) { SEpiRes<true> SE{p.in[1] - (size_t)MP * DM, p.out, (bf16_t*)(ws + WS_XN), p.in[17], (float*)(ws + WS_ROWSS)}; small_gemm<8>((const bf16_t*)(ws + WS_CAT), 1024, 0, (const bf16_t*)(ws + WS_WT_OUT), 1024, SE, L); }
.LBB0_724:
	s_cmp_gt_i32 s84, 5
	s_cselect_b64 s[4:5], -1, 0
	s_xor_b64 s[2:3], s[2:3], -1
	s_or_b64 s[2:3], s[4:5], s[2:3]
	s_mov_b64 s[0:1], -1
	s_and_b64 vcc, exec, s[2:3]
	s_cbranch_vccnz .LBB0_778
	s_bfe_u32 s2, s33, 0x10003
	s_cmp_eq_u32 s2, 0
	s_cselect_b64 s[8:9], -1, 0
	s_cmp_eq_u32 s2, 1
	s_cselect_b64 s[2:3], -1, 0
	s_and_b64 vcc, exec, s[2:3]
	s_cbranch_vccz .LBB0_732
	s_cmpk_gt_i32 s33, 0xff
	v_and_b32_e32 v146, 15, v184
	s_cbranch_scc1 .LBB0_731
	s_waitcnt vmcnt(0)
	v_bfe_u32 v7, v184, 6, 2
	v_lshrrev_b32_e32 v6, 6, v184
	v_lshlrev_b32_e32 v0, 9, v7
	v_mov_b32_e32 v1, 0
	v_lshl_add_u64 v[2:3], s[50:51], 0, v[0:1]
	v_lshlrev_b32_e32 v0, 12, v6
	v_lshlrev_b32_e32 v6, 4, v184
	s_add_u32 s4, s54, 0xfc000000
	v_lshrrev_b32_e32 v12, 8, v184
	v_and_b32_e32 v10, 48, v184
	v_mov_b32_e32 v11, v1
	v_and_b32_e32 v6, 0x3f0, v6
	s_addc_u32 s5, s55, -1
	v_lshl_add_u64 v[4:5], v[2:3], 0, v[10:11]
	v_add_u32_e32 v11, 0, v6
	v_lshlrev_b32_e32 v9, 14, v12
	s_add_u32 s6, s50, 0xf00000
	v_add_u32_e32 v8, 0, v9
	v_lshlrev_b32_e32 v13, 10, v7
	v_add_u32_e32 v14, v11, v9
	v_add_u32_e32 v11, v11, v0
	v_mbcnt_lo_u32_b32 v0, -1, 0
	s_addc_u32 s7, s51, 0
	s_mov_b64 s[0:1], 0x9b40000
	v_add3_u32 v6, v8, v13, v6
	v_cmp_eq_u32_e32 vcc, 0, v10
	v_lshlrev_b32_e32 v9, 1, v12
	v_lshlrev_b32_e32 v10, 5, v12
	v_add_u32_e32 v12, v14, v13
	v_mbcnt_hi_u32_b32 v13, -1, v0
	s_add_u32 s10, s50, 0xbed8000
	v_lshl_add_u64 v[2:3], v[4:5], 0, s[0:1]
	s_mov_b64 s[0:1], 0x680000
	v_lshrrev_b32_e32 v7, 3, v184
	v_lshrrev_b32_e32 v8, 2, v184
	v_and_b32_e32 v0, 64, v13
	s_addc_u32 s11, s51, 0
	v_lshl_add_u64 v[4:5], v[4:5], 0, s[0:1]
	v_and_or_b32 v7, v7, 16, v146
	v_and_b32_e32 v8, 28, v8
	v_lshl_add_u32 v9, s33, 2, v9
	s_lshl_b32 s12, s86, 2
	v_lshl_add_u32 v10, s33, 6, v10
	s_lshl_b32 s13, s86, 6
	s_mov_b32 s14, 0x8000
	v_xor_b32_e32 v14, 16, v13
	v_add_u32_e32 v15, 64, v0
	v_xor_b32_e32 v16, 32, v13
	s_mov_b32 s15, s33
	s_branch .LBB0_729

; #define LAS __attribute__((address_space(3)))
; template <int KS, class Epi>
; __device__ __forceinline__ void small_gemm(const bf16_t* __restrict__ A, int lda, int a_grp_step, const bf16_t* __restrict__ Bt, int N, const Epi& E, LAS unsigned char* lds) {
;     constexpr int K = KS * 128;
;     const int lane = threadIdx.x & 63, wid = threadIdx.x >> 6, fr = lane & 15, fq = lane >> 4, th = wid >> 2, kq = wid & 3;
;     LAS f32x4* red = (LAS f32x4*)lds;
;     const int ntile = 16 * (N >> 5);
;     for (int pair = blockIdx.x; pair * 2 < ntile; pair += gridDim.x) {
;         const int tile = pair * 2 + th, tr = tile & 15, tc = tile >> 4, row0 = MP + tr * 32, col0 = tc * 32;
;         const bf16_t* ap = A + (size_t)(row0 + fr) * lda + (col0 >> 8) * a_grp_step + kq * (KS * 32) + 8 * fq;
;         const bf16_t* bp = Bt + (size_t)(col0 + fr) * K + kq * (KS * 32) + 8 * fq;
; __global__ void __launch_bounds__(512, 2) mega(Params p) {
;     ...
;     if (PH_ON(7)) { pg8::StaticOrder S; const bool sfirst = (blockIdx.x & 1) != 0;
;         if (sfirst) { SEpiUG SE{(bf16_t*)(ws + WS_U), (bf16_t*)(ws + WS_SG), (const float*)(ws + WS_ROWSS)}; small_gemm<8>((const bf16_t*)(ws + WS_XN), 1024, 0, (const bf16_t*)(ws + WS_WT_INC), 2048, SE, L); }
.LBB0_832:
	s_cmp_lt_i32 s84, 8
	s_cselect_b64 s[10:11], -1, 0
	s_and_b64 s[0:1], s[10:11], s[2:3]
	s_andn2_b64 vcc, exec, s[0:1]
	s_cbranch_vccnz .LBB0_938
	s_bfe_u32 s0, s33, 0x10003
	s_cmp_eq_u32 s0, 0
	s_cselect_b64 s[12:13], -1, 0
	s_cmp_eq_u32 s0, 1
	s_cselect_b64 s[0:1], -1, 0
	s_and_b64 vcc, exec, s[0:1]
	s_cbranch_vccz .LBB0_841
	s_cmpk_gt_i32 s33, 0x1ff
	v_and_b32_e32 v157, 15, v184
	s_cbranch_scc1 .LBB0_842
	s_waitcnt vmcnt(0)
	v_bfe_u32 v8, v184, 6, 2
	v_lshrrev_b32_e32 v6, 8, v184
	v_lshrrev_b32_e32 v7, 6, v184
	v_lshlrev_b32_e32 v0, 9, v8
	s_waitcnt lgkmcnt(0)
	v_mov_b32_e32 v1, 0
	v_lshl_add_u64 v[4:5], s[50:51], 0, v[0:1]
	v_lshlrev_b32_e32 v0, 12, v7
	v_lshlrev_b32_e32 v7, 4, v184
	v_lshlrev_b32_e32 v10, 14, v6
	v_and_b32_e32 v7, 0x3f0, v7
	v_add_u32_e32 v11, 0, v10
	v_lshlrev_b32_e32 v8, 10, v8
	s_add_u32 s4, s50, 0x3000000
	v_and_b32_e32 v2, 48, v184
	v_mov_b32_e32 v3, v1
	v_add_u32_e32 v9, 0, v7
	v_add3_u32 v12, v11, v8, v7
	v_lshrrev_b32_e32 v7, 3, v184
	s_addc_u32 s5, s51, 0
	v_lshl_add_u64 v[4:5], v[4:5], 0, v[2:3]
	s_mov_b64 s[0:1], 0xf00000
	v_and_or_b32 v13, v7, 16, v157
	v_lshrrev_b32_e32 v7, 2, v184
	s_add_u32 s6, s50, 0xbed8000
	v_lshl_add_u64 v[2:3], v[4:5], 0, s[0:1]
	s_mov_b64 s[0:1], 0x880000
	v_and_b32_e32 v14, 28, v7
	v_add_u32_e32 v7, v9, v10
	v_lshlrev_b32_e32 v10, 1, v6
	v_lshlrev_b32_e32 v6, 5, v6
	s_addc_u32 s7, s51, 0
	v_lshl_add_u64 v[4:5], v[4:5], 0, s[0:1]
	v_lshl_add_u32 v15, s33, 2, v10
	s_lshl_b32 s8, s86, 2
	v_lshl_add_u32 v16, s33, 6, v6
	s_lshl_b32 s9, s86, 6
	s_mov_b32 s14, 0x8000
	v_add_u32_e32 v17, v9, v0
	v_add_u32_e32 v18, v7, v8
	v_mov_b32_e32 v19, 0x358637bd
	s_mov_b32 s15, 0x800000
	s_movk_i32 s16, 0x3ff
	s_mov_b32 s17, s33
	s_branch .LBB0_837

; #define LAS __attribute__((address_space(3)))
; template <int KS, class Epi>
; __device__ __forceinline__ void small_gemm(const bf16_t* __restrict__ A, int lda, int a_grp_step, const bf16_t* __restrict__ Bt, int N, const Epi& E, LAS unsigned char* lds) {
;     constexpr int K = KS * 128;
;     const int lane = threadIdx.x & 63, wid = threadIdx.x >> 6, fr = lane & 15, fq = lane >> 4, th = wid >> 2, kq = wid & 3;
;     LAS f32x4* red = (LAS f32x4*)lds;
;     const int ntile = 16 * (N >> 5);
;     for (int pair = blockIdx.x; pair * 2 < ntile; pair += gridDim.x) {
;         const int tile = pair * 2 + th, tr = tile & 15, tc = tile >> 4, row0 = MP + tr * 32, col0 = tc * 32;
;         const bf16_t* ap = A + (size_t)(row0 + fr) * lda + (col0 >> 8) * a_grp_step + kq * (KS * 32) + 8 * fq;
;         const bf16_t* bp = Bt + (size_t)(col0 + fr) * K + kq * (KS * 32) + 8 * fq;
; __global__ void __launch_bounds__(512, 2) mega(Params p) {
;     ...
;     if (PH_ON(9)) { pg8::StaticOrder S; const bool sfirst = (blockIdx.x & 1) != 0;
;         if (sfirst) { SEpiM SE{p.in[20], (const bf16_t*)(ws + WS_SG), (bf16_t*)(ws + WS_MM)}; small_gemm<2>((const bf16_t*)(ws + WS_POOL), 1024, 256, (const bf16_t*)(ws + WS_WT_GRP), 1024, SE, L); }
.LBB0_1369:
	s_cmp_lt_i32 s84, 10
	s_cselect_b64 s[4:5], -1, 0
	s_and_b64 s[0:1], s[4:5], s[2:3]
	s_andn2_b64 vcc, exec, s[0:1]
	s_cbranch_vccnz .LBB0_1401
	s_bfe_u32 s0, s33, 0x10003
	s_cmp_eq_u32 s0, 0
	s_cselect_b64 s[6:7], -1, 0
	s_cmp_eq_u32 s0, 1
	s_cselect_b64 s[0:1], -1, 0
	s_and_b64 vcc, exec, s[0:1]
	s_cbranch_vccz .LBB0_1375
	s_cmpk_gt_i32 s33, 0xff
	v_and_b32_e32 v148, 15, v184
	s_cbranch_scc1 .LBB0_1374
	s_waitcnt vmcnt(0)
	v_bfe_u32 v8, v184, 6, 2
	s_add_u32 s2, s50, 0x7200000
	v_lshrrev_b32_e32 v5, 8, v184
	s_waitcnt lgkmcnt(0)
	v_mov_b32_e32 v1, 0
	v_lshlrev_b32_e32 v0, 7, v8
	s_addc_u32 s3, s51, 0
	v_lshrrev_b32_e32 v7, 6, v184
	v_and_b32_e32 v9, 63, v184
	v_lshl_add_u64 v[2:3], s[50:51], 0, v[0:1]
	v_and_b32_e32 v0, 48, v184
	v_lshlrev_b32_e32 v11, 14, v5
	s_add_u32 s8, s50, 0x9b40000
	v_bfe_u32 v10, v184, 4, 2
	v_lshl_add_u64 v[2:3], v[2:3], 0, v[0:1]
	v_lshlrev_b32_e32 v0, 12, v7
	v_lshlrev_b32_e32 v7, 4, v9
	v_add_u32_e32 v9, 0, v11
	v_lshlrev_b32_e32 v14, 10, v8
	s_addc_u32 s9, s51, 0
	v_lshlrev_b32_e32 v4, 6, v8
	v_lshlrev_b32_e32 v6, 3, v10
	v_add_u32_e32 v13, 0, v7
	v_add3_u32 v8, v9, v14, v7
	v_lshrrev_b32_e32 v7, 3, v184
	v_lshrrev_b32_e32 v9, 2, v184
	v_lshlrev_b32_e32 v10, 2, v10
	s_add_u32 s10, s50, 0x5100000
	s_mov_b64 s[0:1], 0xc80000
	v_and_or_b32 v9, v9, 16, v10
	v_add_u32_e32 v15, v13, v11
	v_and_or_b32 v10, v7, 16, v148
	v_lshlrev_b32_e32 v7, 1, v5
	v_lshlrev_b32_e32 v5, 5, v5
	s_addc_u32 s11, s51, 0
	v_lshl_add_u64 v[2:3], v[2:3], 0, s[0:1]
	v_lshl_add_u32 v11, s33, 2, v7
	s_lshl_b32 s0, s86, 2
	v_lshl_add_u32 v12, s33, 6, v5
	s_lshl_b32 s1, s86, 6
	v_lshlrev_b32_e32 v4, 1, v4
	v_mov_b32_e32 v5, v1
	v_lshlrev_b32_e32 v6, 1, v6
	v_mov_b32_e32 v7, v1
	s_mov_b32 s12, 0x8000
	s_movk_i32 s13, 0x2000
	v_add_u32_e32 v13, v13, v0
	v_add_u32_e32 v14, v15, v14
	s_mov_b32 s14, s33

; #define LAS __attribute__((address_space(3)))
; template <int KS, class Epi>
; __device__ __forceinline__ void small_gemm(const bf16_t* __restrict__ A, int lda, int a_grp_step, const bf16_t* __restrict__ Bt, int N, const Epi& E, LAS unsigned char* lds) {
;     constexpr int K = KS * 128;
;     const int lane = threadIdx.x & 63, wid = threadIdx.x >> 6, fr = lane & 15, fq = lane >> 4, th = wid >> 2, kq = wid & 3;
;     LAS f32x4* red = (LAS f32x4*)lds;
;     const int ntile = 16 * (N >> 5);
;     for (int pair = blockIdx.x; pair * 2 < ntile; pair += gridDim.x) {
;         const int tile = pair * 2 + th, tr = tile & 15, tc = tile >> 4, row0 = MP + tr * 32, col0 = tc * 32;
;         const bf16_t* ap = A + (size_t)(row0 + fr) * lda + (col0 >> 8) * a_grp_step + kq * (KS * 32) + 8 * fq;
;         const bf16_t* bp = Bt + (size_t)(col0 + fr) * K + kq * (KS * 32) + 8 * fq;
; __global__ void __launch_bounds__(512, 2) mega(Params p) {
;     ...
;     if (PH_ON(10)) { pg8::StaticOrder S; const bool sfirst = (blockIdx.x & 1) != 0;
;         if (sfirst) { SEpiRes<false> SE{nullptr, p.out, (bf16_t*)(ws + WS_XN), nullptr, nullptr}; small_gemm<8>((const bf16_t*)(ws + WS_MM), 1024, 0, (const bf16_t*)(ws + WS_WT_OUTC), 1024, SE, L); }
.LBB0_1455:
	s_cmp_gt_i32 s84, 10
	s_cselect_b64 s[4:5], -1, 0
	s_xor_b64 s[2:3], s[2:3], -1
	s_or_b64 s[2:3], s[4:5], s[2:3]
	s_mov_b64 s[0:1], -1
	s_and_b64 vcc, exec, s[2:3]
	s_cbranch_vccnz .LBB0_1487
	s_bfe_u32 s4, s33, 0x10003
	s_cmp_eq_u32 s4, 0
	s_cselect_b64 s[2:3], -1, 0
	s_cmp_eq_u32 s4, 1
	s_cselect_b64 s[4:5], -1, 0
	s_and_b64 vcc, exec, s[4:5]
	s_waitcnt vmcnt(0)
	v_and_b32_e32 v6, 15, v184
	s_cbranch_vccz .LBB0_1461
	s_cmpk_gt_i32 s33, 0xff
	v_and_b32_e32 v146, 15, v184
	s_cbranch_scc1 .LBB0_1460
	v_bfe_u32 v8, v184, 6, 2
	v_lshrrev_b32_e32 v11, 8, v184
	v_lshrrev_b32_e32 v7, 6, v184
	v_lshlrev_b32_e32 v0, 9, v8
	s_waitcnt lgkmcnt(0)
	v_mov_b32_e32 v1, 0
	v_lshl_add_u64 v[4:5], s[50:51], 0, v[0:1]
	v_lshlrev_b32_e32 v0, 12, v7
	v_lshlrev_b32_e32 v7, 4, v184
	v_lshlrev_b32_e32 v9, 14, v11
	v_and_b32_e32 v2, 48, v184
	v_mov_b32_e32 v3, v1
	v_and_b32_e32 v7, 0x3f0, v7
	v_add_u32_e32 v10, 0, v9
	v_lshlrev_b32_e32 v13, 10, v8
	v_lshl_add_u64 v[4:5], v[4:5], 0, v[2:3]
	s_mov_b64 s[4:5], 0x9b40000
	v_add_u32_e32 v12, 0, v7
	v_add3_u32 v7, v10, v13, v7
	v_lshrrev_b32_e32 v10, 3, v184
	s_add_u32 s0, s50, 0xf00000
	v_lshl_add_u64 v[2:3], v[4:5], 0, s[4:5]
	s_mov_b64 s[4:5], 0xd00000
	v_lshrrev_b32_e32 v8, 2, v184
	v_add_u32_e32 v14, v12, v9
	v_and_or_b32 v9, v10, 16, v146
	v_lshlrev_b32_e32 v10, 1, v11
	v_lshlrev_b32_e32 v11, 5, v11
	s_addc_u32 s1, s51, 0
	v_lshl_add_u64 v[4:5], v[4:5], 0, s[4:5]
	v_and_b32_e32 v8, 28, v8
	v_lshl_add_u32 v10, s33, 2, v10
	s_lshl_b32 s4, s86, 2
	v_lshl_add_u32 v11, s33, 6, v11
	s_lshl_b32 s5, s86, 6
	s_mov_b32 s6, 0x8000
	v_add_u32_e32 v12, v12, v0
	v_add_u32_e32 v13, v14, v13
	s_mov_b32 s7, s33
